# prepass tiles: no vmcnt(0) before the LDS-reuse barrier (next tile's loads issue while previous stores drain)
# speedup vs baseline: 1.0022x; 1.0019x over previous
.LBB0_481:
	s_mul_hi_i32 s2, s22, 0x84210843
	s_add_i32 s2, s2, s22
	s_lshr_b32 s3, s2, 31
	s_ashr_i32 s2, s2, 8
	s_add_i32 s4, s2, s3
	s_mul_i32 s2, s4, 0xfffffe10
	s_add_i32 s8, s22, s2
	s_cmpk_gt_i32 s8, 0x17f
	s_cbranch_scc0 .LBB0_492
	s_cmpk_gt_u32 s8, 0x1af
	s_cbranch_scc0 .LBB0_493
	s_ashr_i32 s5, s4, 31
	s_lshl_b64 s[2:3], s[4:5], 22
	v_readlane_b32 s24, v254, 1
	v_readlane_b32 s25, v254, 2
	s_add_u32 s2, s24, s2
	s_mul_i32 s6, s4, 0xffffe100
	s_addc_u32 s3, s25, s3
	s_add_i32 s6, s20, s6
	v_mov_b32_e32 v35, v206
	s_and_b32 s7, s12, 0x3c0
	s_and_b32 s6, s6, 0x7fffff00
	s_addk_i32 s6, 0xe500
	v_lshlrev_b32_e32 v0, 2, v35
	v_ashrrev_i32_e32 v32, 6, v35
	v_add_u32_e32 v6, 0x200, v35
	v_and_b32_e32 v7, 0xfc, v0
	v_add_u32_e32 v2, s7, v32
	v_ashrrev_i32_e32 v33, 6, v6
	v_or_b32_e32 v176, s6, v7
	v_ashrrev_i32_e32 v3, 31, v2
	v_add_u32_e32 v4, s7, v33
	v_lshl_add_u64 v[0:1], v[176:177], 2, s[2:3]
	v_lshlrev_b64 v[2:3], 12, v[2:3]
	v_ashrrev_i32_e32 v5, 31, v4
	v_lshl_add_u64 v[2:3], v[0:1], 0, v[2:3]
	v_lshlrev_b64 v[4:5], 12, v[4:5]
	s_barrier
	v_lshl_add_u64 v[4:5], v[0:1], 0, v[4:5]
	global_load_dwordx4 v[8:11], v[2:3], off nt
	global_load_dwordx4 v[12:15], v[4:5], off nt
	v_add_u32_e32 v3, 0x400, v35
	v_add_u32_e32 v2, 0x600, v35
	v_ashrrev_i32_e32 v44, 6, v3
	v_ashrrev_i32_e32 v46, 6, v2
	v_add_u32_e32 v4, s7, v44
	v_add_u32_e32 v16, s7, v46
	v_ashrrev_i32_e32 v5, 31, v4
	v_ashrrev_i32_e32 v17, 31, v16
	v_lshlrev_b64 v[4:5], 12, v[4:5]
	v_lshlrev_b64 v[16:17], 12, v[16:17]
	v_lshl_add_u64 v[4:5], v[0:1], 0, v[4:5]
	v_lshl_add_u64 v[20:21], v[0:1], 0, v[16:17]
	global_load_dwordx4 v[16:19], v[4:5], off nt
	s_nop 0
	global_load_dwordx4 v[20:23], v[20:21], off nt
	v_add_u32_e32 v4, 0x800, v35
	v_add_u32_e32 v24, 0xa00, v35
	v_ashrrev_i32_e32 v47, 6, v4
	v_ashrrev_i32_e32 v48, 6, v24
	v_add_u32_e32 v4, s7, v47
	v_add_u32_e32 v24, s7, v48
	v_ashrrev_i32_e32 v5, 31, v4
	v_ashrrev_i32_e32 v25, 31, v24
	v_lshlrev_b64 v[4:5], 12, v[4:5]
	v_lshlrev_b64 v[24:25], 12, v[24:25]
	v_lshl_add_u64 v[4:5], v[0:1], 0, v[4:5]
	v_lshl_add_u64 v[28:29], v[0:1], 0, v[24:25]
	global_load_dwordx4 v[24:27], v[4:5], off nt
	s_nop 0
	global_load_dwordx4 v[28:31], v[28:29], off nt
	v_add_u32_e32 v4, 0xc00, v35
	v_ashrrev_i32_e32 v49, 6, v4
	v_add_u32_e32 v4, s7, v49
	v_ashrrev_i32_e32 v5, 31, v4
	v_lshlrev_b64 v[4:5], 12, v[4:5]
	v_lshl_add_u64 v[4:5], v[0:1], 0, v[4:5]
	global_load_dwordx4 v[36:39], v[4:5], off nt
	v_add_u32_e32 v4, 0xe00, v35
	v_ashrrev_i32_e32 v50, 6, v4
	v_add_u32_e32 v4, s7, v50
	v_ashrrev_i32_e32 v5, 31, v4
	v_lshlrev_b64 v[4:5], 12, v[4:5]
	v_lshl_add_u64 v[0:1], v[0:1], 0, v[4:5]
	global_load_dwordx4 v[40:43], v[0:1], off nt
	s_lshl_b64 s[2:3], s[4:5], 21
	v_lshlrev_b32_e32 v0, 2, v7
	v_mad_u64_u32 v[4:5], s[24:25], v32, s15, v[0:1]
	s_add_u32 s5, s43, s2
	v_readlane_b32 s2, v254, 23
	v_mad_u64_u32 v[32:33], s[24:25], v33, s15, v[0:1]
	v_mad_u64_u32 v[44:45], s[24:25], v44, s15, v[0:1]
	s_addc_u32 s9, s2, s3
	v_readlane_b32 s26, v254, 3
	v_readlane_b32 s27, v254, 4
	v_readlane_b32 s28, v254, 5
	v_readlane_b32 s29, v254, 6
	v_readlane_b32 s30, v254, 7
	v_readlane_b32 s31, v254, 8
	s_waitcnt vmcnt(7)
	ds_write2_b32 v4, v8, v9 offset1:1
	ds_write2_b32 v4, v10, v11 offset0:2 offset1:3
	s_waitcnt vmcnt(6)
	ds_write2_b32 v32, v12, v13 offset1:1
	ds_write2_b32 v32, v14, v15 offset0:2 offset1:3
	s_waitcnt vmcnt(5)
	ds_write2_b32 v44, v16, v17 offset1:1
	ds_write2_b32 v44, v18, v19 offset0:2 offset1:3
	v_mad_u64_u32 v[4:5], s[2:3], v46, s15, v[0:1]
	s_waitcnt vmcnt(4)
	ds_write2_b32 v4, v20, v21 offset1:1
	ds_write2_b32 v4, v22, v23 offset0:2 offset1:3
	v_mad_u64_u32 v[4:5], s[2:3], v47, s15, v[0:1]
	s_waitcnt vmcnt(3)
	ds_write2_b32 v4, v24, v25 offset1:1
	ds_write2_b32 v4, v26, v27 offset0:2 offset1:3
	v_mad_u64_u32 v[4:5], s[2:3], v48, s15, v[0:1]
	s_waitcnt vmcnt(2)
	ds_write2_b32 v4, v28, v29 offset1:1
	ds_write2_b32 v4, v30, v31 offset0:2 offset1:3
	v_mad_u64_u32 v[4:5], s[2:3], v49, s15, v[0:1]
	v_mad_u64_u32 v[0:1], s[2:3], v50, s15, v[0:1]
	s_waitcnt vmcnt(1)
	ds_write2_b32 v4, v36, v37 offset1:1
	ds_write2_b32 v4, v38, v39 offset0:2 offset1:3
	s_waitcnt vmcnt(0)
	ds_write2_b32 v0, v40, v41 offset1:1
	ds_write2_b32 v0, v42, v43 offset0:2 offset1:3
	v_lshlrev_b32_e32 v0, 3, v35
	s_lshl_b32 s2, s7, 1
	v_and_b32_e32 v0, 56, v0
	s_add_u32 s2, s5, s2
	v_ashrrev_i32_e32 v1, 3, v35
	v_mul_u32_u24_e32 v7, 0x404, v0
	s_addc_u32 s3, s9, 0
	v_lshlrev_b32_e32 v176, 1, v0
	v_add_u32_e32 v0, s6, v1
	v_lshl_add_u64 v[4:5], s[2:3], 0, v[176:177]
	v_cmp_gt_i32_e32 vcc, s93, v0
	s_waitcnt lgkmcnt(0)
	s_barrier
	s_and_saveexec_b64 s[2:3], vcc
	s_cbranch_execz .LBB0_485
	v_lshl_add_u32 v1, v1, 2, v7
	ds_read_b32 v8, v1
	ds_read_b32 v9, v1 offset:1028
	s_waitcnt lgkmcnt(0)
	v_cvt_pk_bf16_f32 v8, v8, v9
	ds_read_b32 v9, v1 offset:2056
	ds_read_b32 v10, v1 offset:3084
	s_waitcnt lgkmcnt(0)
	v_cvt_pk_bf16_f32 v9, v9, v10
	ds_read_b32 v10, v1 offset:4112
	ds_read_b32 v11, v1 offset:5140
	s_waitcnt lgkmcnt(0)
	v_cvt_pk_bf16_f32 v10, v10, v11
	ds_read_b32 v11, v1 offset:6168
	ds_read_b32 v1, v1 offset:7196
	s_waitcnt lgkmcnt(0)
	v_cvt_pk_bf16_f32 v11, v11, v1
	v_ashrrev_i32_e32 v1, 31, v0
	v_lshlrev_b64 v[0:1], 11, v[0:1]
	v_lshl_add_u64 v[0:1], v[4:5], 0, v[0:1]
	global_store_dwordx4 v[0:1], v[8:11], off sc1

.LBB0_494:
	s_add_i32 s2, s8, 0xfffffe80
	s_lshr_b32 s72, s2, 4
	s_mul_i32 s2, s4, 3
	s_mul_hi_i32 s3, s4, 3
	s_add_u32 s2, s2, s72
	s_addc_u32 s3, s3, 0
	s_lshl_b64 s[2:3], s[2:3], 20
	s_add_u32 s2, s58, s2
	s_mul_i32 s5, s4, 0xffff8400
	v_mov_b32_e32 v35, v206
	s_addc_u32 s3, s59, s3
	s_add_i32 s5, s12, s5
	s_and_b32 s6, s5, 0xc0
	v_lshlrev_b32_e32 v0, 2, v35
	s_and_b32 s5, s5, 0x300
	v_and_b32_e32 v7, 0xfc, v0
	v_ashrrev_i32_e32 v32, 6, v35
	v_add_u32_e32 v6, 0x200, v35
	v_or_b32_e32 v0, s5, v7
	v_add_u32_e32 v2, s6, v32
	v_ashrrev_i32_e32 v33, 6, v6
	v_lshlrev_b32_e32 v176, 2, v0
	v_ashrrev_i32_e32 v3, 31, v2
	v_add_u32_e32 v4, s6, v33
	v_lshl_add_u64 v[0:1], s[2:3], 0, v[176:177]
	v_lshlrev_b64 v[2:3], 12, v[2:3]
	v_ashrrev_i32_e32 v5, 31, v4
	v_lshl_add_u64 v[2:3], v[0:1], 0, v[2:3]
	v_lshlrev_b64 v[4:5], 12, v[4:5]
	s_barrier
	v_lshl_add_u64 v[4:5], v[0:1], 0, v[4:5]
	global_load_dwordx4 v[8:11], v[2:3], off nt
	global_load_dwordx4 v[12:15], v[4:5], off nt
	v_add_u32_e32 v3, 0x400, v35
	v_add_u32_e32 v2, 0x600, v35
	v_ashrrev_i32_e32 v44, 6, v3
	v_ashrrev_i32_e32 v45, 6, v2
	v_add_u32_e32 v4, s6, v44
	v_add_u32_e32 v16, s6, v45
	v_ashrrev_i32_e32 v5, 31, v4
	v_ashrrev_i32_e32 v17, 31, v16
	v_lshlrev_b64 v[4:5], 12, v[4:5]
	v_lshlrev_b64 v[16:17], 12, v[16:17]
	v_lshl_add_u64 v[4:5], v[0:1], 0, v[4:5]
	v_lshl_add_u64 v[20:21], v[0:1], 0, v[16:17]
	global_load_dwordx4 v[16:19], v[4:5], off nt
	s_nop 0
	global_load_dwordx4 v[20:23], v[20:21], off nt
	v_add_u32_e32 v4, 0x800, v35
	v_add_u32_e32 v24, 0xa00, v35
	v_ashrrev_i32_e32 v46, 6, v4
	v_ashrrev_i32_e32 v47, 6, v24
	v_add_u32_e32 v4, s6, v46
	v_add_u32_e32 v24, s6, v47
	v_ashrrev_i32_e32 v5, 31, v4
	v_ashrrev_i32_e32 v25, 31, v24
	v_lshlrev_b64 v[4:5], 12, v[4:5]
	v_lshlrev_b64 v[24:25], 12, v[24:25]
	v_lshl_add_u64 v[4:5], v[0:1], 0, v[4:5]
	v_lshl_add_u64 v[28:29], v[0:1], 0, v[24:25]
	global_load_dwordx4 v[24:27], v[4:5], off nt
	s_nop 0
	global_load_dwordx4 v[28:31], v[28:29], off nt
	v_add_u32_e32 v4, 0xc00, v35
	v_ashrrev_i32_e32 v48, 6, v4
	v_add_u32_e32 v4, s6, v48
	v_ashrrev_i32_e32 v5, 31, v4
	v_lshlrev_b64 v[4:5], 12, v[4:5]
	v_lshl_add_u64 v[4:5], v[0:1], 0, v[4:5]
	global_load_dwordx4 v[36:39], v[4:5], off nt
	v_add_u32_e32 v4, 0xe00, v35
	v_ashrrev_i32_e32 v49, 6, v4
	v_add_u32_e32 v4, s6, v49
	v_ashrrev_i32_e32 v5, 31, v4
	v_lshlrev_b64 v[4:5], 12, v[4:5]
	v_lshl_add_u64 v[0:1], v[0:1], 0, v[4:5]
	global_load_dwordx4 v[40:43], v[0:1], off nt
	s_mul_i32 s9, s4, 0x180000
	v_lshlrev_b32_e32 v0, 2, v7
	s_mul_hi_i32 s7, s4, 0x180000
	v_mad_u64_u32 v[4:5], s[2:3], v32, s15, v[0:1]
	v_mad_u64_u32 v[32:33], s[2:3], v33, s15, v[0:1]
	s_add_u32 s9, s35, s9
	s_addc_u32 s7, s42, s7
	s_lshl_b64 s[2:3], s[72:73], 19
	s_add_u32 s9, s9, s2
	s_addc_u32 s7, s7, s3
	s_waitcnt vmcnt(7)
	ds_write2_b32 v4, v8, v9 offset1:1
	ds_write2_b32 v4, v10, v11 offset0:2 offset1:3
	s_waitcnt vmcnt(6)
	ds_write2_b32 v32, v12, v13 offset1:1
	ds_write2_b32 v32, v14, v15 offset0:2 offset1:3
	v_mad_u64_u32 v[4:5], s[2:3], v44, s15, v[0:1]
	s_waitcnt vmcnt(5)
	ds_write2_b32 v4, v16, v17 offset1:1
	ds_write2_b32 v4, v18, v19 offset0:2 offset1:3
	v_mad_u64_u32 v[4:5], s[2:3], v45, s15, v[0:1]
	s_waitcnt vmcnt(4)
	ds_write2_b32 v4, v20, v21 offset1:1
	ds_write2_b32 v4, v22, v23 offset0:2 offset1:3
	v_mad_u64_u32 v[4:5], s[2:3], v46, s15, v[0:1]
	s_waitcnt vmcnt(3)
	ds_write2_b32 v4, v24, v25 offset1:1
	ds_write2_b32 v4, v26, v27 offset0:2 offset1:3
	v_mad_u64_u32 v[4:5], s[2:3], v47, s15, v[0:1]
	s_waitcnt vmcnt(2)
	ds_write2_b32 v4, v28, v29 offset1:1
	ds_write2_b32 v4, v30, v31 offset0:2 offset1:3
	v_mad_u64_u32 v[4:5], s[2:3], v48, s15, v[0:1]
	v_mad_u64_u32 v[0:1], s[2:3], v49, s15, v[0:1]
	s_waitcnt vmcnt(1)
	ds_write2_b32 v4, v36, v37 offset1:1
	ds_write2_b32 v4, v38, v39 offset0:2 offset1:3
	s_waitcnt vmcnt(0)
	ds_write2_b32 v0, v40, v41 offset1:1
	ds_write2_b32 v0, v42, v43 offset0:2 offset1:3
	v_lshlrev_b32_e32 v0, 3, v35
	s_lshl_b32 s2, s6, 1
	v_and_b32_e32 v0, 56, v0
	s_add_u32 s2, s9, s2
	v_ashrrev_i32_e32 v1, 3, v35
	v_mul_u32_u24_e32 v7, 0x404, v0
	s_addc_u32 s3, s7, 0
	v_lshlrev_b32_e32 v176, 1, v0
	v_add_u32_e32 v0, s5, v1
	v_lshl_add_u64 v[4:5], s[2:3], 0, v[176:177]
	v_cmp_gt_i32_e32 vcc, s93, v0
	s_waitcnt lgkmcnt(0)
	s_barrier
	s_and_saveexec_b64 s[2:3], vcc
	s_cbranch_execz .LBB0_496
	v_lshl_add_u32 v1, v1, 2, v7
	ds_read_b32 v8, v1
	ds_read_b32 v9, v1 offset:1028
	s_waitcnt lgkmcnt(0)
	v_cvt_pk_bf16_f32 v8, v8, v9
	ds_read_b32 v9, v1 offset:2056
	ds_read_b32 v10, v1 offset:3084
	s_waitcnt lgkmcnt(0)
	v_cvt_pk_bf16_f32 v9, v9, v10
	ds_read_b32 v10, v1 offset:4112
	ds_read_b32 v11, v1 offset:5140
	s_waitcnt lgkmcnt(0)
	v_cvt_pk_bf16_f32 v10, v10, v11
	ds_read_b32 v11, v1 offset:6168
	ds_read_b32 v1, v1 offset:7196
	s_waitcnt lgkmcnt(0)
	v_cvt_pk_bf16_f32 v11, v11, v1
	v_ashrrev_i32_e32 v1, 31, v0
	v_lshlrev_b64 v[0:1], 9, v[0:1]
	v_lshl_add_u64 v[0:1], v[4:5], 0, v[0:1]
	global_store_dwordx4 v[0:1], v[8:11], off sc1

.LBB0_504:
	s_bfe_u32 s2, s8, 0x4001b
	s_add_i32 s2, s8, s2
	s_sext_i32_i16 s3, s2
	s_and_b32 s2, s2, 0xfff0
	s_sub_i32 s2, s8, s2
	s_mul_i32 s6, s4, 0x1710000
	s_mul_hi_i32 s5, s4, 0x1710000
	s_add_u32 s6, s46, s6
	v_mov_b32_e32 v38, v206
	s_addc_u32 s7, s47, s5
	s_lshl_b32 s3, s3, 4
	s_and_b32 s23, s3, 0xffffff00
	v_lshlrev_b32_e32 v0, 2, v38
	v_and_b32_e32 v39, 0xfc, v0
	v_or_b32_e32 v0, s23, v39
	s_sext_i32_i16 s2, s2
	v_ashrrev_i32_e32 v1, 31, v0
	s_lshl_b32 s2, s2, 6
	v_cmp_gt_i32_e32 vcc, s16, v0
	v_lshl_add_u64 v[32:33], v[0:1], 2, s[6:7]
	v_mov_b32_e32 v0, 0
	v_ashrrev_i32_e32 v40, 6, v38
	v_mov_b32_e32 v4, 0
	v_mov_b32_e32 v5, 0
	v_mov_b32_e32 v6, 0
	v_mov_b32_e32 v7, 0
	s_barrier
	s_and_saveexec_b64 s[6:7], vcc
	s_cbranch_execz .LBB0_506
	v_add_u32_e32 v1, s2, v40
	v_mad_i64_i32 v[2:3], s[8:9], v1, s17, v[32:33]
	global_load_dwordx4 v[4:7], v[2:3], off nt
